# v35 + attention tile loop back edge rotated (7.11): slot rotation, next-tile bookkeeping and K/V global load issue moved in front of the loop-back barrier
# baseline (speedup 1.0000x reference)
; template <int DQK, bool CAUSAL, bool ROPE> ...
;     ...
;     for (int j = 0; j < ntiles; ++j) {
;         const bool more = j + 1 < ntiles;
;         const int vnext = vcur == 2 ? 0 : vcur + 1;
;         if (more) AT_LOAD(j + 1);
;         if (grp == 1 && j > 0) AT_PV(j - 1, vprev);
;         AT_QKSM(j);
;         if (grp == 0) AT_PV(j, vcur);
;         if (more) AT_STORE((j + 1) & 1, vnext);
;         __syncthreads();
;         vprev = vcur; vcur = vnext;
.LBB0_891:
	s_add_i32 s92, s92, 64
	s_mov_b64 s[4:5], 0x2000
	v_subrev_u32_e32 v251, 64, v251
	v_lshl_add_u64 v[228:229], v[228:229], 0, s[94:95]
	v_lshl_add_u64 v[226:227], v[226:227], 0, s[94:95]
	v_lshl_add_u64 v[224:225], v[224:225], 0, s[4:5]
	v_lshl_add_u64 v[222:223], v[222:223], 0, s[80:81]
	s_cmp_eq_u32 s65, s92
	v_lshl_add_u64 v[220:221], v[220:221], 0, s[80:81]
	s_cbranch_scc1 .Lrot_exit
	s_mov_b32 s0, s71
	s_mov_b32 s71, s1
	s_mov_b32 s1, s2
	s_add_i32 s2, s1, 1
	s_cmp_lt_u32 s2, s33
	s_cselect_b64 s[66:67], -1, 0
	s_add_i32 s4, s1, 2
	s_cmp_ge_u32 s4, s33
	s_cbranch_scc1 .Lrot_noload
	s_bitcmp1_b32 s1, 0
	s_cbranch_scc1 .Lrot_ldx
	global_load_dwordx4 v[166:169], v222, s[96:97]
	global_load_dwordx4 v[170:173], v220, s[96:97]
	global_load_dwordx4 v[180:183], v224, s[96:97]
	global_load_dwordx4 v[184:187], v228, s[96:97]
	global_load_dwordx4 v[188:191], v226, s[96:97]
	s_branch .Lrot_noload

; template <int DQK, bool CAUSAL, bool ROPE> ...
;     ...
;         __syncthreads();
;         vprev = vcur; vcur = vnext;
.Lrot_noload:
	s_waitcnt lgkmcnt(0)
	s_barrier
	s_branch .LBB0_885
